# filter GEMM runs only the two K-tiles that hold data (the other two are zero padding)
# speedup vs baseline: 1.0116x; 1.0116x over previous
.LBB0_309:
	s_or_b64 exec, exec, s[48:49]
	s_and_b64 s[4:5], exec, vcc
	v_mov_b32_e32 v0, 0
	s_or_b64 s[20:21], s[4:5], s[20:21]
	s_mov_b32 s12, 0
	s_mov_b64 s[4:5], 0
	s_mov_b64 s[48:49], -1
	v_mov_b32_e32 v1, v0
	v_mov_b32_e32 v2, v0
	v_mov_b32_e32 v3, v0
	v_mov_b32_e32 v4, v0
	v_mov_b32_e32 v5, v0
	v_mov_b32_e32 v6, v0
	v_mov_b32_e32 v7, v0
	v_mov_b32_e32 v8, v0
	v_mov_b32_e32 v9, v0
	v_mov_b32_e32 v10, v0
	v_mov_b32_e32 v11, v0
	v_mov_b32_e32 v16, v0
	v_mov_b32_e32 v17, v0
	v_mov_b32_e32 v18, v0
	v_mov_b32_e32 v19, v0
	v_mov_b32_e32 v24, v0
	v_mov_b32_e32 v25, v0
	v_mov_b32_e32 v26, v0
	v_mov_b32_e32 v27, v0
	v_mov_b32_e32 v32, v0
	v_mov_b32_e32 v33, v0
	v_mov_b32_e32 v34, v0
	v_mov_b32_e32 v35, v0
	v_mov_b32_e32 v40, v0
	v_mov_b32_e32 v41, v0
	v_mov_b32_e32 v42, v0
	v_mov_b32_e32 v43, v0
	v_mov_b32_e32 v48, v0
	v_mov_b32_e32 v49, v0
	v_mov_b32_e32 v50, v0
	v_mov_b32_e32 v51, v0
	v_mov_b32_e32 v12, v0
	v_mov_b32_e32 v13, v0
	v_mov_b32_e32 v14, v0
	v_mov_b32_e32 v15, v0
	v_mov_b32_e32 v20, v0
	v_mov_b32_e32 v21, v0
	v_mov_b32_e32 v22, v0
	v_mov_b32_e32 v23, v0
	v_mov_b32_e32 v28, v0
	v_mov_b32_e32 v29, v0
	v_mov_b32_e32 v30, v0
	v_mov_b32_e32 v31, v0
	v_mov_b32_e32 v36, v0
	v_mov_b32_e32 v37, v0
	v_mov_b32_e32 v38, v0
	v_mov_b32_e32 v39, v0
	v_mov_b32_e32 v44, v0
	v_mov_b32_e32 v45, v0
	v_mov_b32_e32 v46, v0
	v_mov_b32_e32 v47, v0
	v_mov_b32_e32 v52, v0
	v_mov_b32_e32 v53, v0
	v_mov_b32_e32 v54, v0
	v_mov_b32_e32 v55, v0
	v_mov_b32_e32 v56, v0
	v_mov_b32_e32 v57, v0
	v_mov_b32_e32 v58, v0
	v_mov_b32_e32 v59, v0
	v_mov_b32_e32 v60, v0
	v_mov_b32_e32 v61, v0
	v_mov_b32_e32 v62, v0
	v_mov_b32_e32 v63, v0
	v_mov_b32_e32 v64, v0
	v_mov_b32_e32 v65, v0
	v_mov_b32_e32 v66, v0
	v_mov_b32_e32 v67, v0
	v_mov_b32_e32 v68, v0
	v_mov_b32_e32 v69, v0
	v_mov_b32_e32 v70, v0
	v_mov_b32_e32 v71, v0
	v_mov_b32_e32 v72, v0
	v_mov_b32_e32 v73, v0
	v_mov_b32_e32 v74, v0
	v_mov_b32_e32 v75, v0
	v_mov_b32_e32 v80, v0
	v_mov_b32_e32 v81, v0
	v_mov_b32_e32 v82, v0
	v_mov_b32_e32 v83, v0
	v_mov_b32_e32 v88, v0
	v_mov_b32_e32 v89, v0
	v_mov_b32_e32 v90, v0
	v_mov_b32_e32 v91, v0
	v_mov_b32_e32 v96, v0
	v_mov_b32_e32 v97, v0
	v_mov_b32_e32 v98, v0
	v_mov_b32_e32 v99, v0
	v_mov_b32_e32 v104, v0
	v_mov_b32_e32 v105, v0
	v_mov_b32_e32 v106, v0
	v_mov_b32_e32 v107, v0
	v_mov_b32_e32 v112, v0
	v_mov_b32_e32 v113, v0
	v_mov_b32_e32 v114, v0
	v_mov_b32_e32 v115, v0
	v_mov_b32_e32 v76, v0
	v_mov_b32_e32 v77, v0
	v_mov_b32_e32 v78, v0
	v_mov_b32_e32 v79, v0
	v_mov_b32_e32 v84, v0
	v_mov_b32_e32 v85, v0
	v_mov_b32_e32 v86, v0
	v_mov_b32_e32 v87, v0
	v_mov_b32_e32 v92, v0
	v_mov_b32_e32 v93, v0
	v_mov_b32_e32 v94, v0
	v_mov_b32_e32 v95, v0
	v_mov_b32_e32 v100, v0
	v_mov_b32_e32 v101, v0
	v_mov_b32_e32 v102, v0
	v_mov_b32_e32 v103, v0
	v_mov_b32_e32 v108, v0
	v_mov_b32_e32 v109, v0
	v_mov_b32_e32 v110, v0
	v_mov_b32_e32 v111, v0
	v_mov_b32_e32 v116, v0
	v_mov_b32_e32 v117, v0
	v_mov_b32_e32 v118, v0
	v_mov_b32_e32 v119, v0
	v_mov_b32_e32 v120, v0
	v_mov_b32_e32 v121, v0
	v_mov_b32_e32 v122, v0
	v_mov_b32_e32 v123, v0
	v_mov_b32_e32 v124, v0
	v_mov_b32_e32 v125, v0
	v_mov_b32_e32 v126, v0
	v_mov_b32_e32 v127, v0
